# forget-gate cumsum on the last two workgroups rewritten: loads batched and issued two banks ahead with counted vmcnt, bpermute scans batched 8 steps at a time (was one memory round trip per step and t
# speedup vs baseline: 1.0789x; 1.0104x over previous
.LBB0_744:
	v_readlane_b32 s4, v239, 10
	v_readlane_b32 s5, v239, 11
	s_cmp_lt_i32 s4, 4
	v_readlane_b32 s6, v239, 12
	v_readlane_b32 s7, v239, 13
	s_cselect_b64 s[4:5], -1, 0
	s_and_b64 s[6:7], s[4:5], s[0:1]
	s_andn2_b64 vcc, exec, s[6:7]
	s_cbranch_vccnz .LBB0_849
	s_add_i32 s0, s33, -2
	s_cmp_ge_i32 s2, s0
	s_cbranch_scc0 .LBB0_755
	v_readfirstlane_b32 s3, v166
	s_sub_i32 s4, s2, s0
	s_lshr_b32 s8, s3, 6
	s_mov_b32 s5, 0
	s_lshl_b64 s[0:1], s[4:5], 12
	s_lshl_b32 s4, s8, 9
	s_add_u32 s0, s0, s4
	v_bfe_u32 v0, v166, 4, 2
	s_addc_u32 s1, s1, 0
	v_or_b32_e32 v2, s0, v0
	v_mov_b32_e32 v3, s1
	v_and_b32_e32 v8, 15, v166
	v_lshlrev_b64 v[2:3], 6, v[2:3]
	v_lshl_or_b32 v2, v8, 2, v2
	v_mov_b32_e32 v1, 0
	v_lshl_add_u64 v[2:3], s[92:93], 0, v[2:3]
	s_mov_b64 s[0:1], 0x8100800
	v_lshl_add_u64 v[4:5], v[2:3], 0, s[0:1]
	s_mov_b64 s[0:1], 0
	v_mov_b32_e32 v6, v1
	v_lshl_add_u64 v[10:11], v[4:5], 0, s[0:1]
	global_load_dword v32, v[10:11], off offset:-2048
	global_load_dword v33, v[10:11], off offset:-1792
	global_load_dword v34, v[10:11], off offset:-1536
	global_load_dword v35, v[10:11], off offset:-1280
	global_load_dword v36, v[10:11], off offset:-1024
	global_load_dword v37, v[10:11], off offset:-768
	global_load_dword v38, v[10:11], off offset:-512
	global_load_dword v39, v[10:11], off offset:-256
	global_load_dword v40, v[10:11], off
	global_load_dword v41, v[10:11], off offset:256
	global_load_dword v42, v[10:11], off offset:512
	global_load_dword v43, v[10:11], off offset:768
	global_load_dword v44, v[10:11], off offset:1024
	global_load_dword v45, v[10:11], off offset:1280
	global_load_dword v46, v[10:11], off offset:1536
	global_load_dword v47, v[10:11], off offset:1792
	s_add_u32 s0, s0, 0x1000
	s_addc_u32 s1, s1, 0
	v_lshl_add_u64 v[10:11], v[4:5], 0, s[0:1]
	global_load_dword v48, v[10:11], off offset:-2048
	global_load_dword v49, v[10:11], off offset:-1792
	global_load_dword v50, v[10:11], off offset:-1536
	global_load_dword v51, v[10:11], off offset:-1280
	global_load_dword v52, v[10:11], off offset:-1024
	global_load_dword v53, v[10:11], off offset:-768
	global_load_dword v54, v[10:11], off offset:-512
	global_load_dword v55, v[10:11], off offset:-256
	global_load_dword v56, v[10:11], off
	global_load_dword v57, v[10:11], off offset:256
	global_load_dword v58, v[10:11], off offset:512
	global_load_dword v59, v[10:11], off offset:768
	global_load_dword v60, v[10:11], off offset:1024
	global_load_dword v61, v[10:11], off offset:1280
	global_load_dword v62, v[10:11], off offset:1536
	global_load_dword v63, v[10:11], off offset:1792
	s_add_u32 s0, s0, 0x1000
	s_addc_u32 s1, s1, 0
	v_lshl_add_u64 v[10:11], v[4:5], 0, s[0:1]
	global_load_dword v64, v[10:11], off offset:-2048
	global_load_dword v65, v[10:11], off offset:-1792
	global_load_dword v66, v[10:11], off offset:-1536
	global_load_dword v67, v[10:11], off offset:-1280
	global_load_dword v68, v[10:11], off offset:-1024
	global_load_dword v69, v[10:11], off offset:-768
	global_load_dword v70, v[10:11], off offset:-512
	global_load_dword v71, v[10:11], off offset:-256
	global_load_dword v72, v[10:11], off
	global_load_dword v73, v[10:11], off offset:256
	global_load_dword v74, v[10:11], off offset:512
	global_load_dword v75, v[10:11], off offset:768
	global_load_dword v76, v[10:11], off offset:1024
	global_load_dword v77, v[10:11], off offset:1280
	global_load_dword v78, v[10:11], off offset:1536
	global_load_dword v79, v[10:11], off offset:1792
	s_add_u32 s0, s0, 0x1000
	s_addc_u32 s1, s1, 0
	s_waitcnt vmcnt(32)
	v_add_f32_e32 v6, v6, v32
	v_add_f32_e32 v6, v6, v33
	v_add_f32_e32 v6, v6, v34
	v_add_f32_e32 v6, v6, v35
	v_add_f32_e32 v6, v6, v36
	v_add_f32_e32 v6, v6, v37
	v_add_f32_e32 v6, v6, v38
	v_add_f32_e32 v6, v6, v39
	v_add_f32_e32 v6, v6, v40
	v_add_f32_e32 v6, v6, v41
	v_add_f32_e32 v6, v6, v42
	v_add_f32_e32 v6, v6, v43
	v_add_f32_e32 v6, v6, v44
	v_add_f32_e32 v6, v6, v45
	v_add_f32_e32 v6, v6, v46
	v_add_f32_e32 v6, v6, v47
	v_lshl_add_u64 v[10:11], v[4:5], 0, s[0:1]
	global_load_dword v32, v[10:11], off offset:-2048
	global_load_dword v33, v[10:11], off offset:-1792
	global_load_dword v34, v[10:11], off offset:-1536
	global_load_dword v35, v[10:11], off offset:-1280
	global_load_dword v36, v[10:11], off offset:-1024
	global_load_dword v37, v[10:11], off offset:-768
	global_load_dword v38, v[10:11], off offset:-512
	global_load_dword v39, v[10:11], off offset:-256
	global_load_dword v40, v[10:11], off
	global_load_dword v41, v[10:11], off offset:256
	global_load_dword v42, v[10:11], off offset:512
	global_load_dword v43, v[10:11], off offset:768
	global_load_dword v44, v[10:11], off offset:1024
	global_load_dword v45, v[10:11], off offset:1280
	global_load_dword v46, v[10:11], off offset:1536
	global_load_dword v47, v[10:11], off offset:1792
	s_add_u32 s0, s0, 0x1000
	s_addc_u32 s1, s1, 0
	s_waitcnt vmcnt(32)
	v_add_f32_e32 v6, v6, v48
	v_add_f32_e32 v6, v6, v49
	v_add_f32_e32 v6, v6, v50
	v_add_f32_e32 v6, v6, v51
	v_add_f32_e32 v6, v6, v52
	v_add_f32_e32 v6, v6, v53
	v_add_f32_e32 v6, v6, v54
	v_add_f32_e32 v6, v6, v55
	v_add_f32_e32 v6, v6, v56
	v_add_f32_e32 v6, v6, v57
	v_add_f32_e32 v6, v6, v58
	v_add_f32_e32 v6, v6, v59
	v_add_f32_e32 v6, v6, v60
	v_add_f32_e32 v6, v6, v61
	v_add_f32_e32 v6, v6, v62
	v_add_f32_e32 v6, v6, v63
	v_lshl_add_u64 v[10:11], v[4:5], 0, s[0:1]
	global_load_dword v48, v[10:11], off offset:-2048
	global_load_dword v49, v[10:11], off offset:-1792
	global_load_dword v50, v[10:11], off offset:-1536
	global_load_dword v51, v[10:11], off offset:-1280
	global_load_dword v52, v[10:11], off offset:-1024
	global_load_dword v53, v[10:11], off offset:-768
	global_load_dword v54, v[10:11], off offset:-512
	global_load_dword v55, v[10:11], off offset:-256
	global_load_dword v56, v[10:11], off
	global_load_dword v57, v[10:11], off offset:256
	global_load_dword v58, v[10:11], off offset:512
	global_load_dword v59, v[10:11], off offset:768
	global_load_dword v60, v[10:11], off offset:1024
	global_load_dword v61, v[10:11], off offset:1280
	global_load_dword v62, v[10:11], off offset:1536
	global_load_dword v63, v[10:11], off offset:1792
	s_add_u32 s0, s0, 0x1000
	s_addc_u32 s1, s1, 0
	s_waitcnt vmcnt(32)
	v_add_f32_e32 v6, v6, v64
	v_add_f32_e32 v6, v6, v65
	v_add_f32_e32 v6, v6, v66
	v_add_f32_e32 v6, v6, v67
	v_add_f32_e32 v6, v6, v68
	v_add_f32_e32 v6, v6, v69
	v_add_f32_e32 v6, v6, v70
	v_add_f32_e32 v6, v6, v71
	v_add_f32_e32 v6, v6, v72
	v_add_f32_e32 v6, v6, v73
	v_add_f32_e32 v6, v6, v74
	v_add_f32_e32 v6, v6, v75
	v_add_f32_e32 v6, v6, v76
	v_add_f32_e32 v6, v6, v77
	v_add_f32_e32 v6, v6, v78
	v_add_f32_e32 v6, v6, v79
	v_lshl_add_u64 v[10:11], v[4:5], 0, s[0:1]
	global_load_dword v64, v[10:11], off offset:-2048
	global_load_dword v65, v[10:11], off offset:-1792
	global_load_dword v66, v[10:11], off offset:-1536
	global_load_dword v67, v[10:11], off offset:-1280
	global_load_dword v68, v[10:11], off offset:-1024
	global_load_dword v69, v[10:11], off offset:-768
	global_load_dword v70, v[10:11], off offset:-512
	global_load_dword v71, v[10:11], off offset:-256
	global_load_dword v72, v[10:11], off
	global_load_dword v73, v[10:11], off offset:256
	global_load_dword v74, v[10:11], off offset:512
	global_load_dword v75, v[10:11], off offset:768
	global_load_dword v76, v[10:11], off offset:1024
	global_load_dword v77, v[10:11], off offset:1280
	global_load_dword v78, v[10:11], off offset:1536
	global_load_dword v79, v[10:11], off offset:1792
	s_add_u32 s0, s0, 0x1000
	s_addc_u32 s1, s1, 0
	s_waitcnt vmcnt(32)
	v_add_f32_e32 v6, v6, v32
	v_add_f32_e32 v6, v6, v33
	v_add_f32_e32 v6, v6, v34
	v_add_f32_e32 v6, v6, v35
	v_add_f32_e32 v6, v6, v36
	v_add_f32_e32 v6, v6, v37
	v_add_f32_e32 v6, v6, v38
	v_add_f32_e32 v6, v6, v39
	v_add_f32_e32 v6, v6, v40
	v_add_f32_e32 v6, v6, v41
	v_add_f32_e32 v6, v6, v42
	v_add_f32_e32 v6, v6, v43
	v_add_f32_e32 v6, v6, v44
	v_add_f32_e32 v6, v6, v45
	v_add_f32_e32 v6, v6, v46
	v_add_f32_e32 v6, v6, v47
	v_lshl_add_u64 v[10:11], v[4:5], 0, s[0:1]
	global_load_dword v32, v[10:11], off offset:-2048
	global_load_dword v33, v[10:11], off offset:-1792
	global_load_dword v34, v[10:11], off offset:-1536
	global_load_dword v35, v[10:11], off offset:-1280
	global_load_dword v36, v[10:11], off offset:-1024
	global_load_dword v37, v[10:11], off offset:-768
	global_load_dword v38, v[10:11], off offset:-512
	global_load_dword v39, v[10:11], off offset:-256
	global_load_dword v40, v[10:11], off
	global_load_dword v41, v[10:11], off offset:256
	global_load_dword v42, v[10:11], off offset:512
	global_load_dword v43, v[10:11], off offset:768
	global_load_dword v44, v[10:11], off offset:1024
	global_load_dword v45, v[10:11], off offset:1280
	global_load_dword v46, v[10:11], off offset:1536
	global_load_dword v47, v[10:11], off offset:1792
	s_add_u32 s0, s0, 0x1000
	s_addc_u32 s1, s1, 0
	s_waitcnt vmcnt(32)
	v_add_f32_e32 v6, v6, v48
	v_add_f32_e32 v6, v6, v49
	v_add_f32_e32 v6, v6, v50
	v_add_f32_e32 v6, v6, v51
	v_add_f32_e32 v6, v6, v52
	v_add_f32_e32 v6, v6, v53
	v_add_f32_e32 v6, v6, v54
	v_add_f32_e32 v6, v6, v55
	v_add_f32_e32 v6, v6, v56
	v_add_f32_e32 v6, v6, v57
	v_add_f32_e32 v6, v6, v58
	v_add_f32_e32 v6, v6, v59
	v_add_f32_e32 v6, v6, v60
	v_add_f32_e32 v6, v6, v61
	v_add_f32_e32 v6, v6, v62
	v_add_f32_e32 v6, v6, v63
	v_lshl_add_u64 v[10:11], v[4:5], 0, s[0:1]
	global_load_dword v48, v[10:11], off offset:-2048
	global_load_dword v49, v[10:11], off offset:-1792
	global_load_dword v50, v[10:11], off offset:-1536
	global_load_dword v51, v[10:11], off offset:-1280
	global_load_dword v52, v[10:11], off offset:-1024
	global_load_dword v53, v[10:11], off offset:-768
	global_load_dword v54, v[10:11], off offset:-512
	global_load_dword v55, v[10:11], off offset:-256
	global_load_dword v56, v[10:11], off
	global_load_dword v57, v[10:11], off offset:256
	global_load_dword v58, v[10:11], off offset:512
	global_load_dword v59, v[10:11], off offset:768
	global_load_dword v60, v[10:11], off offset:1024
	global_load_dword v61, v[10:11], off offset:1280
	global_load_dword v62, v[10:11], off offset:1536
	global_load_dword v63, v[10:11], off offset:1792
	s_add_u32 s0, s0, 0x1000
	s_addc_u32 s1, s1, 0
	s_waitcnt vmcnt(32)
	v_add_f32_e32 v6, v6, v64
	v_add_f32_e32 v6, v6, v65
	v_add_f32_e32 v6, v6, v66
	v_add_f32_e32 v6, v6, v67
	v_add_f32_e32 v6, v6, v68
	v_add_f32_e32 v6, v6, v69
	v_add_f32_e32 v6, v6, v70
	v_add_f32_e32 v6, v6, v71
	v_add_f32_e32 v6, v6, v72
	v_add_f32_e32 v6, v6, v73
	v_add_f32_e32 v6, v6, v74
	v_add_f32_e32 v6, v6, v75
	v_add_f32_e32 v6, v6, v76
	v_add_f32_e32 v6, v6, v77
	v_add_f32_e32 v6, v6, v78
	v_add_f32_e32 v6, v6, v79
	s_waitcnt vmcnt(16)
	v_add_f32_e32 v6, v6, v32
	v_add_f32_e32 v6, v6, v33
	v_add_f32_e32 v6, v6, v34
	v_add_f32_e32 v6, v6, v35
	v_add_f32_e32 v6, v6, v36
	v_add_f32_e32 v6, v6, v37
	v_add_f32_e32 v6, v6, v38
	v_add_f32_e32 v6, v6, v39
	v_add_f32_e32 v6, v6, v40
	v_add_f32_e32 v6, v6, v41
	v_add_f32_e32 v6, v6, v42
	v_add_f32_e32 v6, v6, v43
	v_add_f32_e32 v6, v6, v44
	v_add_f32_e32 v6, v6, v45
	v_add_f32_e32 v6, v6, v46
	v_add_f32_e32 v6, v6, v47
	s_waitcnt vmcnt(0)
	v_add_f32_e32 v6, v6, v48
	v_add_f32_e32 v6, v6, v49
	v_add_f32_e32 v6, v6, v50
	v_add_f32_e32 v6, v6, v51
	v_add_f32_e32 v6, v6, v52
	v_add_f32_e32 v6, v6, v53
	v_add_f32_e32 v6, v6, v54
	v_add_f32_e32 v6, v6, v55
	v_add_f32_e32 v6, v6, v56
	v_add_f32_e32 v6, v6, v57
	v_add_f32_e32 v6, v6, v58
	v_add_f32_e32 v6, v6, v59
	v_add_f32_e32 v6, v6, v60
	v_add_f32_e32 v6, v6, v61
	v_add_f32_e32 v6, v6, v62
	v_add_f32_e32 v6, v6, v63
	v_mbcnt_lo_u32_b32 v4, -1, 0
	v_mbcnt_hi_u32_b32 v5, -1, v4
	v_and_b32_e32 v4, 64, v5
	v_xor_b32_e32 v7, 16, v5
	v_add_u32_e32 v9, 64, v4
	v_cmp_lt_i32_e32 vcc, v7, v9
	v_xor_b32_e32 v10, 32, v5
	s_nop 0
	v_cndmask_b32_e32 v7, v5, v7, vcc
	v_lshlrev_b32_e32 v7, 2, v7
	ds_bpermute_b32 v7, v7, v6
	v_cmp_lt_i32_e32 vcc, v10, v9
	s_waitcnt lgkmcnt(0)
	v_add_f32_e32 v6, v6, v7
	v_cndmask_b32_e32 v7, v5, v10, vcc
	v_lshlrev_b32_e32 v7, 2, v7
	ds_bpermute_b32 v7, v7, v6
	v_cmp_eq_u32_e32 vcc, 0, v0
	s_and_saveexec_b64 s[0:1], vcc
	s_cbranch_execz .LBB0_750
	s_and_b32 s9, s3, 0xffffffc0
	s_add_i32 s9, s9, 0
	s_waitcnt lgkmcnt(0)
	v_add_f32_e32 v6, v6, v7
	v_lshl_add_u32 v7, v8, 2, s9
	ds_write_b32 v7, v6

.LBB0_759:
	v_add_u32_e32 v6, -16, v5
	v_cmp_lt_i32_e64 s[0:1], v6, v4
	v_subrev_u32_e32 v7, 32, v5
	s_lshl_b32 s3, s33, 4
	v_cndmask_b32_e64 v6, v6, v5, s[0:1]
	v_cmp_lt_i32_e64 s[0:1], v7, v4
	v_or_b32_e32 v4, v8, v4
	v_lshlrev_b32_e32 v6, 2, v6
	v_cndmask_b32_e64 v5, v7, v5, s[0:1]
	v_lshlrev_b32_e32 v7, 2, v5
	v_mov_b32_e32 v5, 0xc0
	v_lshl_or_b32 v9, v4, 2, v5
	v_lshl_or_b32 v4, s2, 4, v8
	v_subrev_u32_e32 v4, s3, v4
	v_add_u32_e32 v4, 32, v4
	v_ashrrev_i32_e32 v5, 31, v4
	v_lshlrev_b64 v[4:5], 12, v[4:5]
	v_lshl_add_u64 v[4:5], v[4:5], 0, s[4:5]
	v_cmp_lt_u32_e64 s[0:1], 1, v0
	v_lshl_add_u64 v[0:1], v[4:5], 0, v[0:1]
	s_mov_b64 s[4:5], 0x8100400
	v_lshl_add_u64 v[0:1], v[0:1], 3, s[94:95]
	v_lshl_add_u64 v[2:3], v[2:3], 0, s[4:5]
	s_mov_b64 s[8:9], 0
	s_mov_b32 s3, 0xbfb8aa3b
	s_movk_i32 s12, 0x7fff
	s_mov_b32 s13, 0x1900000
	s_mov_b64 s[10:11], 0x800
	v_add_co_u32_e64 v0, s[4:5], s13, v0
	s_nop 1
	v_addc_co_u32_e64 v1, s[4:5], 0, v1, s[4:5]
	global_load_dword v32, v[2:3], off offset:-1024
	global_load_dword v33, v[2:3], off offset:-768
	global_load_dword v34, v[2:3], off offset:-512
	global_load_dword v35, v[2:3], off offset:-256
	global_load_dword v36, v[2:3], off
	global_load_dword v37, v[2:3], off offset:256
	global_load_dword v38, v[2:3], off offset:512
	global_load_dword v39, v[2:3], off offset:768
	v_lshl_add_u64 v[2:3], v[2:3], 0, s[10:11]
	global_load_dword v40, v[2:3], off offset:-1024
	global_load_dword v41, v[2:3], off offset:-768
	global_load_dword v42, v[2:3], off offset:-512
	global_load_dword v43, v[2:3], off offset:-256
	global_load_dword v44, v[2:3], off
	global_load_dword v45, v[2:3], off offset:256
	global_load_dword v46, v[2:3], off offset:512
	global_load_dword v47, v[2:3], off offset:768
	v_lshl_add_u64 v[2:3], v[2:3], 0, s[10:11]
	global_load_dword v48, v[2:3], off offset:-1024
	global_load_dword v49, v[2:3], off offset:-768
	global_load_dword v50, v[2:3], off offset:-512
	global_load_dword v51, v[2:3], off offset:-256
	global_load_dword v52, v[2:3], off
	global_load_dword v53, v[2:3], off offset:256
	global_load_dword v54, v[2:3], off offset:512
	global_load_dword v55, v[2:3], off offset:768
	v_lshl_add_u64 v[2:3], v[2:3], 0, s[10:11]
	global_load_dword v56, v[2:3], off offset:-1024
	global_load_dword v57, v[2:3], off offset:-768
	global_load_dword v58, v[2:3], off offset:-512
	global_load_dword v59, v[2:3], off offset:-256
	global_load_dword v60, v[2:3], off
	global_load_dword v61, v[2:3], off offset:256
	global_load_dword v62, v[2:3], off offset:512
	global_load_dword v63, v[2:3], off offset:768
	v_lshl_add_u64 v[2:3], v[2:3], 0, s[10:11]
	s_waitcnt vmcnt(16)
.Lcs_loop:
	s_waitcnt vmcnt(40)
	ds_bpermute_b32 v64, v6, v32
	ds_bpermute_b32 v65, v6, v33
	ds_bpermute_b32 v66, v6, v34
	ds_bpermute_b32 v67, v6, v35
	ds_bpermute_b32 v68, v6, v36
	ds_bpermute_b32 v69, v6, v37
	ds_bpermute_b32 v70, v6, v38
	ds_bpermute_b32 v71, v6, v39
	s_waitcnt lgkmcnt(7)
	v_add_f32_e32 v64, v32, v64
	v_cndmask_b32_e32 v32, v64, v32, vcc
	s_waitcnt lgkmcnt(6)
	v_add_f32_e32 v65, v33, v65
	v_cndmask_b32_e32 v33, v65, v33, vcc
	s_waitcnt lgkmcnt(5)
	v_add_f32_e32 v66, v34, v66
	v_cndmask_b32_e32 v34, v66, v34, vcc
	s_waitcnt lgkmcnt(4)
	v_add_f32_e32 v67, v35, v67
	v_cndmask_b32_e32 v35, v67, v35, vcc
	s_waitcnt lgkmcnt(3)
	v_add_f32_e32 v68, v36, v68
	v_cndmask_b32_e32 v36, v68, v36, vcc
	s_waitcnt lgkmcnt(2)
	v_add_f32_e32 v69, v37, v69
	v_cndmask_b32_e32 v37, v69, v37, vcc
	s_waitcnt lgkmcnt(1)
	v_add_f32_e32 v70, v38, v70
	v_cndmask_b32_e32 v38, v70, v38, vcc
	s_waitcnt lgkmcnt(0)
	v_add_f32_e32 v71, v39, v71
	v_cndmask_b32_e32 v39, v71, v39, vcc
	ds_bpermute_b32 v64, v7, v32
	ds_bpermute_b32 v65, v7, v33
	ds_bpermute_b32 v66, v7, v34
	ds_bpermute_b32 v67, v7, v35
	ds_bpermute_b32 v68, v7, v36
	ds_bpermute_b32 v69, v7, v37
	ds_bpermute_b32 v70, v7, v38
	ds_bpermute_b32 v71, v7, v39
	s_waitcnt lgkmcnt(7)
	v_add_f32_e32 v64, v32, v64
	v_cndmask_b32_e64 v32, v32, v64, s[0:1]
	s_waitcnt lgkmcnt(6)
	v_add_f32_e32 v65, v33, v65
	v_cndmask_b32_e64 v33, v33, v65, s[0:1]
	s_waitcnt lgkmcnt(5)
	v_add_f32_e32 v66, v34, v66
	v_cndmask_b32_e64 v34, v34, v66, s[0:1]
	s_waitcnt lgkmcnt(4)
	v_add_f32_e32 v67, v35, v67
	v_cndmask_b32_e64 v35, v35, v67, s[0:1]
	s_waitcnt lgkmcnt(3)
	v_add_f32_e32 v68, v36, v68
	v_cndmask_b32_e64 v36, v36, v68, s[0:1]
	s_waitcnt lgkmcnt(2)
	v_add_f32_e32 v69, v37, v69
	v_cndmask_b32_e64 v37, v37, v69, s[0:1]
	s_waitcnt lgkmcnt(1)
	v_add_f32_e32 v70, v38, v70
	v_cndmask_b32_e64 v38, v38, v70, s[0:1]
	s_waitcnt lgkmcnt(0)
	v_add_f32_e32 v71, v39, v71
	v_cndmask_b32_e64 v39, v39, v71, s[0:1]
	ds_bpermute_b32 v64, v9, v32
	ds_bpermute_b32 v65, v9, v33
	ds_bpermute_b32 v66, v9, v34
	ds_bpermute_b32 v67, v9, v35
	ds_bpermute_b32 v68, v9, v36
	ds_bpermute_b32 v69, v9, v37
	ds_bpermute_b32 v70, v9, v38
	ds_bpermute_b32 v71, v9, v39
	v_lshl_add_u64 v[4:5], v[0:1], 0, s[8:9]
	v_mov_b32_e32 v72, v10
	s_waitcnt lgkmcnt(7)
	v_add_f32_e32 v73, v72, v64
	s_waitcnt lgkmcnt(6)
	v_add_f32_e32 v74, v73, v65
	s_waitcnt lgkmcnt(5)
	v_add_f32_e32 v75, v74, v66
	s_waitcnt lgkmcnt(4)
	v_add_f32_e32 v76, v75, v67
	s_waitcnt lgkmcnt(3)
	v_add_f32_e32 v77, v76, v68
	s_waitcnt lgkmcnt(2)
	v_add_f32_e32 v78, v77, v69
	s_waitcnt lgkmcnt(1)
	v_add_f32_e32 v79, v78, v70
	s_waitcnt lgkmcnt(0)
	v_add_f32_e32 v80, v79, v71
	v_mov_b32_e32 v10, v80
	v_add_f32_e32 v12, v72, v32
	v_mul_f32_e32 v13, 0xbfb8aa3b, v12
	v_bfe_u32 v14, v13, 16, 1
	v_add3_u32 v13, v13, v14, s12
	v_and_b32_e32 v14, 0xffff0000, v13
	v_fma_f32 v12, v12, s3, -v14
	v_bfe_u32 v14, v12, 16, 1
	v_add3_u32 v14, v12, v14, s12
	v_and_b32_e32 v14, 0xffff0000, v14
	v_sub_f32_e32 v15, v12, v14
	v_or_b32_sdwa v16, v14, v13 dst_sel:DWORD dst_unused:UNUSED_PAD src0_sel:DWORD src1_sel:WORD_1
	v_bfe_u32 v13, v15, 16, 1
	v_add3_u32 v13, v15, v13, s12
	v_lshrrev_b32_e32 v17, 16, v13
	global_store_dwordx2 v[4:5], v[16:17], off
	v_add_f32_e32 v12, v73, v33
	v_mul_f32_e32 v13, 0xbfb8aa3b, v12
	v_bfe_u32 v14, v13, 16, 1
	v_add3_u32 v13, v13, v14, s12
	v_and_b32_e32 v14, 0xffff0000, v13
	v_fma_f32 v12, v12, s3, -v14
	v_bfe_u32 v14, v12, 16, 1
	v_add3_u32 v14, v12, v14, s12
	v_and_b32_e32 v14, 0xffff0000, v14
	v_sub_f32_e32 v15, v12, v14
	v_or_b32_sdwa v18, v14, v13 dst_sel:DWORD dst_unused:UNUSED_PAD src0_sel:DWORD src1_sel:WORD_1
	v_bfe_u32 v13, v15, 16, 1
	v_add3_u32 v13, v15, v13, s12
	v_lshrrev_b32_e32 v19, 16, v13
	global_store_dwordx2 v[4:5], v[18:19], off offset:32
	v_add_f32_e32 v12, v74, v34
	v_mul_f32_e32 v13, 0xbfb8aa3b, v12
	v_bfe_u32 v14, v13, 16, 1
	v_add3_u32 v13, v13, v14, s12
	v_and_b32_e32 v14, 0xffff0000, v13
	v_fma_f32 v12, v12, s3, -v14
	v_bfe_u32 v14, v12, 16, 1
	v_add3_u32 v14, v12, v14, s12
	v_and_b32_e32 v14, 0xffff0000, v14
	v_sub_f32_e32 v15, v12, v14
	v_or_b32_sdwa v20, v14, v13 dst_sel:DWORD dst_unused:UNUSED_PAD src0_sel:DWORD src1_sel:WORD_1
	v_bfe_u32 v13, v15, 16, 1
	v_add3_u32 v13, v15, v13, s12
	v_lshrrev_b32_e32 v21, 16, v13
	global_store_dwordx2 v[4:5], v[20:21], off offset:64
	v_add_f32_e32 v12, v75, v35
	v_mul_f32_e32 v13, 0xbfb8aa3b, v12
	v_bfe_u32 v14, v13, 16, 1
	v_add3_u32 v13, v13, v14, s12
	v_and_b32_e32 v14, 0xffff0000, v13
	v_fma_f32 v12, v12, s3, -v14
	v_bfe_u32 v14, v12, 16, 1
	v_add3_u32 v14, v12, v14, s12
	v_and_b32_e32 v14, 0xffff0000, v14
	v_sub_f32_e32 v15, v12, v14
	v_or_b32_sdwa v22, v14, v13 dst_sel:DWORD dst_unused:UNUSED_PAD src0_sel:DWORD src1_sel:WORD_1
	v_bfe_u32 v13, v15, 16, 1
	v_add3_u32 v13, v15, v13, s12
	v_lshrrev_b32_e32 v23, 16, v13
	global_store_dwordx2 v[4:5], v[22:23], off offset:96
	v_add_f32_e32 v12, v76, v36
	v_mul_f32_e32 v13, 0xbfb8aa3b, v12
	v_bfe_u32 v14, v13, 16, 1
	v_add3_u32 v13, v13, v14, s12
	v_and_b32_e32 v14, 0xffff0000, v13
	v_fma_f32 v12, v12, s3, -v14
	v_bfe_u32 v14, v12, 16, 1
	v_add3_u32 v14, v12, v14, s12
	v_and_b32_e32 v14, 0xffff0000, v14
	v_sub_f32_e32 v15, v12, v14
	v_or_b32_sdwa v16, v14, v13 dst_sel:DWORD dst_unused:UNUSED_PAD src0_sel:DWORD src1_sel:WORD_1
	v_bfe_u32 v13, v15, 16, 1
	v_add3_u32 v13, v15, v13, s12
	v_lshrrev_b32_e32 v17, 16, v13
	global_store_dwordx2 v[4:5], v[16:17], off offset:128
	v_add_f32_e32 v12, v77, v37
	v_mul_f32_e32 v13, 0xbfb8aa3b, v12
	v_bfe_u32 v14, v13, 16, 1
	v_add3_u32 v13, v13, v14, s12
	v_and_b32_e32 v14, 0xffff0000, v13
	v_fma_f32 v12, v12, s3, -v14
	v_bfe_u32 v14, v12, 16, 1
	v_add3_u32 v14, v12, v14, s12
	v_and_b32_e32 v14, 0xffff0000, v14
	v_sub_f32_e32 v15, v12, v14
	v_or_b32_sdwa v18, v14, v13 dst_sel:DWORD dst_unused:UNUSED_PAD src0_sel:DWORD src1_sel:WORD_1
	v_bfe_u32 v13, v15, 16, 1
	v_add3_u32 v13, v15, v13, s12
	v_lshrrev_b32_e32 v19, 16, v13
	global_store_dwordx2 v[4:5], v[18:19], off offset:160
	v_add_f32_e32 v12, v78, v38
	v_mul_f32_e32 v13, 0xbfb8aa3b, v12
	v_bfe_u32 v14, v13, 16, 1
	v_add3_u32 v13, v13, v14, s12
	v_and_b32_e32 v14, 0xffff0000, v13
	v_fma_f32 v12, v12, s3, -v14
	v_bfe_u32 v14, v12, 16, 1
	v_add3_u32 v14, v12, v14, s12
	v_and_b32_e32 v14, 0xffff0000, v14
	v_sub_f32_e32 v15, v12, v14
	v_or_b32_sdwa v20, v14, v13 dst_sel:DWORD dst_unused:UNUSED_PAD src0_sel:DWORD src1_sel:WORD_1
	v_bfe_u32 v13, v15, 16, 1
	v_add3_u32 v13, v15, v13, s12
	v_lshrrev_b32_e32 v21, 16, v13
	global_store_dwordx2 v[4:5], v[20:21], off offset:192
	v_add_f32_e32 v12, v79, v39
	v_mul_f32_e32 v13, 0xbfb8aa3b, v12
	v_bfe_u32 v14, v13, 16, 1
	v_add3_u32 v13, v13, v14, s12
	v_and_b32_e32 v14, 0xffff0000, v13
	v_fma_f32 v12, v12, s3, -v14
	v_bfe_u32 v14, v12, 16, 1
	v_add3_u32 v14, v12, v14, s12
	v_and_b32_e32 v14, 0xffff0000, v14
	v_sub_f32_e32 v15, v12, v14
	v_or_b32_sdwa v22, v14, v13 dst_sel:DWORD dst_unused:UNUSED_PAD src0_sel:DWORD src1_sel:WORD_1
	v_bfe_u32 v13, v15, 16, 1
	v_add3_u32 v13, v15, v13, s12
	v_lshrrev_b32_e32 v23, 16, v13
	global_store_dwordx2 v[4:5], v[22:23], off offset:224
	s_add_u32 s8, s8, 0x100
	s_addc_u32 s9, s9, 0
	s_waitcnt vmcnt(40)
	ds_bpermute_b32 v64, v6, v40
	ds_bpermute_b32 v65, v6, v41
	ds_bpermute_b32 v66, v6, v42
	ds_bpermute_b32 v67, v6, v43
	ds_bpermute_b32 v68, v6, v44
	ds_bpermute_b32 v69, v6, v45
	ds_bpermute_b32 v70, v6, v46
	ds_bpermute_b32 v71, v6, v47
	s_waitcnt lgkmcnt(7)
	v_add_f32_e32 v64, v40, v64
	v_cndmask_b32_e32 v40, v64, v40, vcc
	s_waitcnt lgkmcnt(6)
	v_add_f32_e32 v65, v41, v65
	v_cndmask_b32_e32 v41, v65, v41, vcc
	s_waitcnt lgkmcnt(5)
	v_add_f32_e32 v66, v42, v66
	v_cndmask_b32_e32 v42, v66, v42, vcc
	s_waitcnt lgkmcnt(4)
	v_add_f32_e32 v67, v43, v67
	v_cndmask_b32_e32 v43, v67, v43, vcc
	s_waitcnt lgkmcnt(3)
	v_add_f32_e32 v68, v44, v68
	v_cndmask_b32_e32 v44, v68, v44, vcc
	s_waitcnt lgkmcnt(2)
	v_add_f32_e32 v69, v45, v69
	v_cndmask_b32_e32 v45, v69, v45, vcc
	s_waitcnt lgkmcnt(1)
	v_add_f32_e32 v70, v46, v70
	v_cndmask_b32_e32 v46, v70, v46, vcc
	s_waitcnt lgkmcnt(0)
	v_add_f32_e32 v71, v47, v71
	v_cndmask_b32_e32 v47, v71, v47, vcc
	ds_bpermute_b32 v64, v7, v40
	ds_bpermute_b32 v65, v7, v41
	ds_bpermute_b32 v66, v7, v42
	ds_bpermute_b32 v67, v7, v43
	ds_bpermute_b32 v68, v7, v44
	ds_bpermute_b32 v69, v7, v45
	ds_bpermute_b32 v70, v7, v46
	ds_bpermute_b32 v71, v7, v47
	s_waitcnt lgkmcnt(7)
	v_add_f32_e32 v64, v40, v64
	v_cndmask_b32_e64 v40, v40, v64, s[0:1]
	s_waitcnt lgkmcnt(6)
	v_add_f32_e32 v65, v41, v65
	v_cndmask_b32_e64 v41, v41, v65, s[0:1]
	s_waitcnt lgkmcnt(5)
	v_add_f32_e32 v66, v42, v66
	v_cndmask_b32_e64 v42, v42, v66, s[0:1]
	s_waitcnt lgkmcnt(4)
	v_add_f32_e32 v67, v43, v67
	v_cndmask_b32_e64 v43, v43, v67, s[0:1]
	s_waitcnt lgkmcnt(3)
	v_add_f32_e32 v68, v44, v68
	v_cndmask_b32_e64 v44, v44, v68, s[0:1]
	s_waitcnt lgkmcnt(2)
	v_add_f32_e32 v69, v45, v69
	v_cndmask_b32_e64 v45, v45, v69, s[0:1]
	s_waitcnt lgkmcnt(1)
	v_add_f32_e32 v70, v46, v70
	v_cndmask_b32_e64 v46, v46, v70, s[0:1]
	s_waitcnt lgkmcnt(0)
	v_add_f32_e32 v71, v47, v71
	v_cndmask_b32_e64 v47, v47, v71, s[0:1]
	ds_bpermute_b32 v64, v9, v40
	ds_bpermute_b32 v65, v9, v41
	ds_bpermute_b32 v66, v9, v42
	ds_bpermute_b32 v67, v9, v43
	ds_bpermute_b32 v68, v9, v44
	ds_bpermute_b32 v69, v9, v45
	ds_bpermute_b32 v70, v9, v46
	ds_bpermute_b32 v71, v9, v47
	v_lshl_add_u64 v[4:5], v[0:1], 0, s[8:9]
	v_mov_b32_e32 v72, v10
	s_waitcnt lgkmcnt(7)
	v_add_f32_e32 v73, v72, v64
	s_waitcnt lgkmcnt(6)
	v_add_f32_e32 v74, v73, v65
	s_waitcnt lgkmcnt(5)
	v_add_f32_e32 v75, v74, v66
	s_waitcnt lgkmcnt(4)
	v_add_f32_e32 v76, v75, v67
	s_waitcnt lgkmcnt(3)
	v_add_f32_e32 v77, v76, v68
	s_waitcnt lgkmcnt(2)
	v_add_f32_e32 v78, v77, v69
	s_waitcnt lgkmcnt(1)
	v_add_f32_e32 v79, v78, v70
	s_waitcnt lgkmcnt(0)
	v_add_f32_e32 v80, v79, v71
	v_mov_b32_e32 v10, v80
	v_add_f32_e32 v12, v72, v40
	v_mul_f32_e32 v13, 0xbfb8aa3b, v12
	v_bfe_u32 v14, v13, 16, 1
	v_add3_u32 v13, v13, v14, s12
	v_and_b32_e32 v14, 0xffff0000, v13
	v_fma_f32 v12, v12, s3, -v14
	v_bfe_u32 v14, v12, 16, 1
	v_add3_u32 v14, v12, v14, s12
	v_and_b32_e32 v14, 0xffff0000, v14
	v_sub_f32_e32 v15, v12, v14
	v_or_b32_sdwa v16, v14, v13 dst_sel:DWORD dst_unused:UNUSED_PAD src0_sel:DWORD src1_sel:WORD_1
	v_bfe_u32 v13, v15, 16, 1
	v_add3_u32 v13, v15, v13, s12
	v_lshrrev_b32_e32 v17, 16, v13
	global_store_dwordx2 v[4:5], v[16:17], off
	v_add_f32_e32 v12, v73, v41
	v_mul_f32_e32 v13, 0xbfb8aa3b, v12
	v_bfe_u32 v14, v13, 16, 1
	v_add3_u32 v13, v13, v14, s12
	v_and_b32_e32 v14, 0xffff0000, v13
	v_fma_f32 v12, v12, s3, -v14
	v_bfe_u32 v14, v12, 16, 1
	v_add3_u32 v14, v12, v14, s12
	v_and_b32_e32 v14, 0xffff0000, v14
	v_sub_f32_e32 v15, v12, v14
	v_or_b32_sdwa v18, v14, v13 dst_sel:DWORD dst_unused:UNUSED_PAD src0_sel:DWORD src1_sel:WORD_1
	v_bfe_u32 v13, v15, 16, 1
	v_add3_u32 v13, v15, v13, s12
	v_lshrrev_b32_e32 v19, 16, v13
	global_store_dwordx2 v[4:5], v[18:19], off offset:32
	v_add_f32_e32 v12, v74, v42
	v_mul_f32_e32 v13, 0xbfb8aa3b, v12
	v_bfe_u32 v14, v13, 16, 1
	v_add3_u32 v13, v13, v14, s12
	v_and_b32_e32 v14, 0xffff0000, v13
	v_fma_f32 v12, v12, s3, -v14
	v_bfe_u32 v14, v12, 16, 1
	v_add3_u32 v14, v12, v14, s12
	v_and_b32_e32 v14, 0xffff0000, v14
	v_sub_f32_e32 v15, v12, v14
	v_or_b32_sdwa v20, v14, v13 dst_sel:DWORD dst_unused:UNUSED_PAD src0_sel:DWORD src1_sel:WORD_1
	v_bfe_u32 v13, v15, 16, 1
	v_add3_u32 v13, v15, v13, s12
	v_lshrrev_b32_e32 v21, 16, v13
	global_store_dwordx2 v[4:5], v[20:21], off offset:64
	v_add_f32_e32 v12, v75, v43
	v_mul_f32_e32 v13, 0xbfb8aa3b, v12
	v_bfe_u32 v14, v13, 16, 1
	v_add3_u32 v13, v13, v14, s12
	v_and_b32_e32 v14, 0xffff0000, v13
	v_fma_f32 v12, v12, s3, -v14
	v_bfe_u32 v14, v12, 16, 1
	v_add3_u32 v14, v12, v14, s12
	v_and_b32_e32 v14, 0xffff0000, v14
	v_sub_f32_e32 v15, v12, v14
	v_or_b32_sdwa v22, v14, v13 dst_sel:DWORD dst_unused:UNUSED_PAD src0_sel:DWORD src1_sel:WORD_1
	v_bfe_u32 v13, v15, 16, 1
	v_add3_u32 v13, v15, v13, s12
	v_lshrrev_b32_e32 v23, 16, v13
	global_store_dwordx2 v[4:5], v[22:23], off offset:96
	v_add_f32_e32 v12, v76, v44
	v_mul_f32_e32 v13, 0xbfb8aa3b, v12
	v_bfe_u32 v14, v13, 16, 1
	v_add3_u32 v13, v13, v14, s12
	v_and_b32_e32 v14, 0xffff0000, v13
	v_fma_f32 v12, v12, s3, -v14
	v_bfe_u32 v14, v12, 16, 1
	v_add3_u32 v14, v12, v14, s12
	v_and_b32_e32 v14, 0xffff0000, v14
	v_sub_f32_e32 v15, v12, v14
	v_or_b32_sdwa v16, v14, v13 dst_sel:DWORD dst_unused:UNUSED_PAD src0_sel:DWORD src1_sel:WORD_1
	v_bfe_u32 v13, v15, 16, 1
	v_add3_u32 v13, v15, v13, s12
	v_lshrrev_b32_e32 v17, 16, v13
	global_store_dwordx2 v[4:5], v[16:17], off offset:128
	v_add_f32_e32 v12, v77, v45
	v_mul_f32_e32 v13, 0xbfb8aa3b, v12
	v_bfe_u32 v14, v13, 16, 1
	v_add3_u32 v13, v13, v14, s12
	v_and_b32_e32 v14, 0xffff0000, v13
	v_fma_f32 v12, v12, s3, -v14
	v_bfe_u32 v14, v12, 16, 1
	v_add3_u32 v14, v12, v14, s12
	v_and_b32_e32 v14, 0xffff0000, v14
	v_sub_f32_e32 v15, v12, v14
	v_or_b32_sdwa v18, v14, v13 dst_sel:DWORD dst_unused:UNUSED_PAD src0_sel:DWORD src1_sel:WORD_1
	v_bfe_u32 v13, v15, 16, 1
	v_add3_u32 v13, v15, v13, s12
	v_lshrrev_b32_e32 v19, 16, v13
	global_store_dwordx2 v[4:5], v[18:19], off offset:160
	v_add_f32_e32 v12, v78, v46
	v_mul_f32_e32 v13, 0xbfb8aa3b, v12
	v_bfe_u32 v14, v13, 16, 1
	v_add3_u32 v13, v13, v14, s12
	v_and_b32_e32 v14, 0xffff0000, v13
	v_fma_f32 v12, v12, s3, -v14
	v_bfe_u32 v14, v12, 16, 1
	v_add3_u32 v14, v12, v14, s12
	v_and_b32_e32 v14, 0xffff0000, v14
	v_sub_f32_e32 v15, v12, v14
	v_or_b32_sdwa v20, v14, v13 dst_sel:DWORD dst_unused:UNUSED_PAD src0_sel:DWORD src1_sel:WORD_1
	v_bfe_u32 v13, v15, 16, 1
	v_add3_u32 v13, v15, v13, s12
	v_lshrrev_b32_e32 v21, 16, v13
	global_store_dwordx2 v[4:5], v[20:21], off offset:192
	v_add_f32_e32 v12, v79, v47
	v_mul_f32_e32 v13, 0xbfb8aa3b, v12
	v_bfe_u32 v14, v13, 16, 1
	v_add3_u32 v13, v13, v14, s12
	v_and_b32_e32 v14, 0xffff0000, v13
	v_fma_f32 v12, v12, s3, -v14
	v_bfe_u32 v14, v12, 16, 1
	v_add3_u32 v14, v12, v14, s12
	v_and_b32_e32 v14, 0xffff0000, v14
	v_sub_f32_e32 v15, v12, v14
	v_or_b32_sdwa v22, v14, v13 dst_sel:DWORD dst_unused:UNUSED_PAD src0_sel:DWORD src1_sel:WORD_1
	v_bfe_u32 v13, v15, 16, 1
	v_add3_u32 v13, v15, v13, s12
	v_lshrrev_b32_e32 v23, 16, v13
	global_store_dwordx2 v[4:5], v[22:23], off offset:224
	s_add_u32 s8, s8, 0x100
	s_addc_u32 s9, s9, 0
	s_waitcnt vmcnt(40)
	global_load_dword v32, v[2:3], off offset:-1024
	global_load_dword v33, v[2:3], off offset:-768
	global_load_dword v34, v[2:3], off offset:-512
	global_load_dword v35, v[2:3], off offset:-256
	global_load_dword v36, v[2:3], off
	global_load_dword v37, v[2:3], off offset:256
	global_load_dword v38, v[2:3], off offset:512
	global_load_dword v39, v[2:3], off offset:768
	v_lshl_add_u64 v[2:3], v[2:3], 0, s[10:11]
	global_load_dword v40, v[2:3], off offset:-1024
	global_load_dword v41, v[2:3], off offset:-768
	global_load_dword v42, v[2:3], off offset:-512
	global_load_dword v43, v[2:3], off offset:-256
	global_load_dword v44, v[2:3], off
	global_load_dword v45, v[2:3], off offset:256
	global_load_dword v46, v[2:3], off offset:512
	global_load_dword v47, v[2:3], off offset:768
	v_lshl_add_u64 v[2:3], v[2:3], 0, s[10:11]
	s_waitcnt vmcnt(40)
	ds_bpermute_b32 v64, v6, v48
	ds_bpermute_b32 v65, v6, v49
	ds_bpermute_b32 v66, v6, v50
	ds_bpermute_b32 v67, v6, v51
	ds_bpermute_b32 v68, v6, v52
	ds_bpermute_b32 v69, v6, v53
	ds_bpermute_b32 v70, v6, v54
	ds_bpermute_b32 v71, v6, v55
	s_waitcnt lgkmcnt(7)
	v_add_f32_e32 v64, v48, v64
	v_cndmask_b32_e32 v48, v64, v48, vcc
	s_waitcnt lgkmcnt(6)
	v_add_f32_e32 v65, v49, v65
	v_cndmask_b32_e32 v49, v65, v49, vcc
	s_waitcnt lgkmcnt(5)
	v_add_f32_e32 v66, v50, v66
	v_cndmask_b32_e32 v50, v66, v50, vcc
	s_waitcnt lgkmcnt(4)
	v_add_f32_e32 v67, v51, v67
	v_cndmask_b32_e32 v51, v67, v51, vcc
	s_waitcnt lgkmcnt(3)
	v_add_f32_e32 v68, v52, v68
	v_cndmask_b32_e32 v52, v68, v52, vcc
	s_waitcnt lgkmcnt(2)
	v_add_f32_e32 v69, v53, v69
	v_cndmask_b32_e32 v53, v69, v53, vcc
	s_waitcnt lgkmcnt(1)
	v_add_f32_e32 v70, v54, v70
	v_cndmask_b32_e32 v54, v70, v54, vcc
	s_waitcnt lgkmcnt(0)
	v_add_f32_e32 v71, v55, v71
	v_cndmask_b32_e32 v55, v71, v55, vcc
	ds_bpermute_b32 v64, v7, v48
	ds_bpermute_b32 v65, v7, v49
	ds_bpermute_b32 v66, v7, v50
	ds_bpermute_b32 v67, v7, v51
	ds_bpermute_b32 v68, v7, v52
	ds_bpermute_b32 v69, v7, v53
	ds_bpermute_b32 v70, v7, v54
	ds_bpermute_b32 v71, v7, v55
	s_waitcnt lgkmcnt(7)
	v_add_f32_e32 v64, v48, v64
	v_cndmask_b32_e64 v48, v48, v64, s[0:1]
	s_waitcnt lgkmcnt(6)
	v_add_f32_e32 v65, v49, v65
	v_cndmask_b32_e64 v49, v49, v65, s[0:1]
	s_waitcnt lgkmcnt(5)
	v_add_f32_e32 v66, v50, v66
	v_cndmask_b32_e64 v50, v50, v66, s[0:1]
	s_waitcnt lgkmcnt(4)
	v_add_f32_e32 v67, v51, v67
	v_cndmask_b32_e64 v51, v51, v67, s[0:1]
	s_waitcnt lgkmcnt(3)
	v_add_f32_e32 v68, v52, v68
	v_cndmask_b32_e64 v52, v52, v68, s[0:1]
	s_waitcnt lgkmcnt(2)
	v_add_f32_e32 v69, v53, v69
	v_cndmask_b32_e64 v53, v53, v69, s[0:1]
	s_waitcnt lgkmcnt(1)
	v_add_f32_e32 v70, v54, v70
	v_cndmask_b32_e64 v54, v54, v70, s[0:1]
	s_waitcnt lgkmcnt(0)
	v_add_f32_e32 v71, v55, v71
	v_cndmask_b32_e64 v55, v55, v71, s[0:1]
	ds_bpermute_b32 v64, v9, v48
	ds_bpermute_b32 v65, v9, v49
	ds_bpermute_b32 v66, v9, v50
	ds_bpermute_b32 v67, v9, v51
	ds_bpermute_b32 v68, v9, v52
	ds_bpermute_b32 v69, v9, v53
	ds_bpermute_b32 v70, v9, v54
	ds_bpermute_b32 v71, v9, v55
	v_lshl_add_u64 v[4:5], v[0:1], 0, s[8:9]
	v_mov_b32_e32 v72, v10
	s_waitcnt lgkmcnt(7)
	v_add_f32_e32 v73, v72, v64
	s_waitcnt lgkmcnt(6)
	v_add_f32_e32 v74, v73, v65
	s_waitcnt lgkmcnt(5)
	v_add_f32_e32 v75, v74, v66
	s_waitcnt lgkmcnt(4)
	v_add_f32_e32 v76, v75, v67
	s_waitcnt lgkmcnt(3)
	v_add_f32_e32 v77, v76, v68
	s_waitcnt lgkmcnt(2)
	v_add_f32_e32 v78, v77, v69
	s_waitcnt lgkmcnt(1)
	v_add_f32_e32 v79, v78, v70
	s_waitcnt lgkmcnt(0)
	v_add_f32_e32 v80, v79, v71
	v_mov_b32_e32 v10, v80
	v_add_f32_e32 v12, v72, v48
	v_mul_f32_e32 v13, 0xbfb8aa3b, v12
	v_bfe_u32 v14, v13, 16, 1
	v_add3_u32 v13, v13, v14, s12
	v_and_b32_e32 v14, 0xffff0000, v13
	v_fma_f32 v12, v12, s3, -v14
	v_bfe_u32 v14, v12, 16, 1
	v_add3_u32 v14, v12, v14, s12
	v_and_b32_e32 v14, 0xffff0000, v14
	v_sub_f32_e32 v15, v12, v14
	v_or_b32_sdwa v16, v14, v13 dst_sel:DWORD dst_unused:UNUSED_PAD src0_sel:DWORD src1_sel:WORD_1
	v_bfe_u32 v13, v15, 16, 1
	v_add3_u32 v13, v15, v13, s12
	v_lshrrev_b32_e32 v17, 16, v13
	global_store_dwordx2 v[4:5], v[16:17], off
	v_add_f32_e32 v12, v73, v49
	v_mul_f32_e32 v13, 0xbfb8aa3b, v12
	v_bfe_u32 v14, v13, 16, 1
	v_add3_u32 v13, v13, v14, s12
	v_and_b32_e32 v14, 0xffff0000, v13
	v_fma_f32 v12, v12, s3, -v14
	v_bfe_u32 v14, v12, 16, 1
	v_add3_u32 v14, v12, v14, s12
	v_and_b32_e32 v14, 0xffff0000, v14
	v_sub_f32_e32 v15, v12, v14
	v_or_b32_sdwa v18, v14, v13 dst_sel:DWORD dst_unused:UNUSED_PAD src0_sel:DWORD src1_sel:WORD_1
	v_bfe_u32 v13, v15, 16, 1
	v_add3_u32 v13, v15, v13, s12
	v_lshrrev_b32_e32 v19, 16, v13
	global_store_dwordx2 v[4:5], v[18:19], off offset:32
	v_add_f32_e32 v12, v74, v50
	v_mul_f32_e32 v13, 0xbfb8aa3b, v12
	v_bfe_u32 v14, v13, 16, 1
	v_add3_u32 v13, v13, v14, s12
	v_and_b32_e32 v14, 0xffff0000, v13
	v_fma_f32 v12, v12, s3, -v14
	v_bfe_u32 v14, v12, 16, 1
	v_add3_u32 v14, v12, v14, s12
	v_and_b32_e32 v14, 0xffff0000, v14
	v_sub_f32_e32 v15, v12, v14
	v_or_b32_sdwa v20, v14, v13 dst_sel:DWORD dst_unused:UNUSED_PAD src0_sel:DWORD src1_sel:WORD_1
	v_bfe_u32 v13, v15, 16, 1
	v_add3_u32 v13, v15, v13, s12
	v_lshrrev_b32_e32 v21, 16, v13
	global_store_dwordx2 v[4:5], v[20:21], off offset:64
	v_add_f32_e32 v12, v75, v51
	v_mul_f32_e32 v13, 0xbfb8aa3b, v12
	v_bfe_u32 v14, v13, 16, 1
	v_add3_u32 v13, v13, v14, s12
	v_and_b32_e32 v14, 0xffff0000, v13
	v_fma_f32 v12, v12, s3, -v14
	v_bfe_u32 v14, v12, 16, 1
	v_add3_u32 v14, v12, v14, s12
	v_and_b32_e32 v14, 0xffff0000, v14
	v_sub_f32_e32 v15, v12, v14
	v_or_b32_sdwa v22, v14, v13 dst_sel:DWORD dst_unused:UNUSED_PAD src0_sel:DWORD src1_sel:WORD_1
	v_bfe_u32 v13, v15, 16, 1
	v_add3_u32 v13, v15, v13, s12
	v_lshrrev_b32_e32 v23, 16, v13
	global_store_dwordx2 v[4:5], v[22:23], off offset:96
	v_add_f32_e32 v12, v76, v52
	v_mul_f32_e32 v13, 0xbfb8aa3b, v12
	v_bfe_u32 v14, v13, 16, 1
	v_add3_u32 v13, v13, v14, s12
	v_and_b32_e32 v14, 0xffff0000, v13
	v_fma_f32 v12, v12, s3, -v14
	v_bfe_u32 v14, v12, 16, 1
	v_add3_u32 v14, v12, v14, s12
	v_and_b32_e32 v14, 0xffff0000, v14
	v_sub_f32_e32 v15, v12, v14
	v_or_b32_sdwa v16, v14, v13 dst_sel:DWORD dst_unused:UNUSED_PAD src0_sel:DWORD src1_sel:WORD_1
	v_bfe_u32 v13, v15, 16, 1
	v_add3_u32 v13, v15, v13, s12
	v_lshrrev_b32_e32 v17, 16, v13
	global_store_dwordx2 v[4:5], v[16:17], off offset:128
	v_add_f32_e32 v12, v77, v53
	v_mul_f32_e32 v13, 0xbfb8aa3b, v12
	v_bfe_u32 v14, v13, 16, 1
	v_add3_u32 v13, v13, v14, s12
	v_and_b32_e32 v14, 0xffff0000, v13
	v_fma_f32 v12, v12, s3, -v14
	v_bfe_u32 v14, v12, 16, 1
	v_add3_u32 v14, v12, v14, s12
	v_and_b32_e32 v14, 0xffff0000, v14
	v_sub_f32_e32 v15, v12, v14
	v_or_b32_sdwa v18, v14, v13 dst_sel:DWORD dst_unused:UNUSED_PAD src0_sel:DWORD src1_sel:WORD_1
	v_bfe_u32 v13, v15, 16, 1
	v_add3_u32 v13, v15, v13, s12
	v_lshrrev_b32_e32 v19, 16, v13
	global_store_dwordx2 v[4:5], v[18:19], off offset:160
	v_add_f32_e32 v12, v78, v54
	v_mul_f32_e32 v13, 0xbfb8aa3b, v12
	v_bfe_u32 v14, v13, 16, 1
	v_add3_u32 v13, v13, v14, s12
	v_and_b32_e32 v14, 0xffff0000, v13
	v_fma_f32 v12, v12, s3, -v14
	v_bfe_u32 v14, v12, 16, 1
	v_add3_u32 v14, v12, v14, s12
	v_and_b32_e32 v14, 0xffff0000, v14
	v_sub_f32_e32 v15, v12, v14
	v_or_b32_sdwa v20, v14, v13 dst_sel:DWORD dst_unused:UNUSED_PAD src0_sel:DWORD src1_sel:WORD_1
	v_bfe_u32 v13, v15, 16, 1
	v_add3_u32 v13, v15, v13, s12
	v_lshrrev_b32_e32 v21, 16, v13
	global_store_dwordx2 v[4:5], v[20:21], off offset:192
	v_add_f32_e32 v12, v79, v55
	v_mul_f32_e32 v13, 0xbfb8aa3b, v12
	v_bfe_u32 v14, v13, 16, 1
	v_add3_u32 v13, v13, v14, s12
	v_and_b32_e32 v14, 0xffff0000, v13
	v_fma_f32 v12, v12, s3, -v14
	v_bfe_u32 v14, v12, 16, 1
	v_add3_u32 v14, v12, v14, s12
	v_and_b32_e32 v14, 0xffff0000, v14
	v_sub_f32_e32 v15, v12, v14
	v_or_b32_sdwa v22, v14, v13 dst_sel:DWORD dst_unused:UNUSED_PAD src0_sel:DWORD src1_sel:WORD_1
	v_bfe_u32 v13, v15, 16, 1
	v_add3_u32 v13, v15, v13, s12
	v_lshrrev_b32_e32 v23, 16, v13
	global_store_dwordx2 v[4:5], v[22:23], off offset:224
	s_add_u32 s8, s8, 0x100
	s_addc_u32 s9, s9, 0
	s_waitcnt vmcnt(40)
	ds_bpermute_b32 v64, v6, v56
	ds_bpermute_b32 v65, v6, v57
	ds_bpermute_b32 v66, v6, v58
	ds_bpermute_b32 v67, v6, v59
	ds_bpermute_b32 v68, v6, v60
	ds_bpermute_b32 v69, v6, v61
	ds_bpermute_b32 v70, v6, v62
	ds_bpermute_b32 v71, v6, v63
	s_waitcnt lgkmcnt(7)
	v_add_f32_e32 v64, v56, v64
	v_cndmask_b32_e32 v56, v64, v56, vcc
	s_waitcnt lgkmcnt(6)
	v_add_f32_e32 v65, v57, v65
	v_cndmask_b32_e32 v57, v65, v57, vcc
	s_waitcnt lgkmcnt(5)
	v_add_f32_e32 v66, v58, v66
	v_cndmask_b32_e32 v58, v66, v58, vcc
	s_waitcnt lgkmcnt(4)
	v_add_f32_e32 v67, v59, v67
	v_cndmask_b32_e32 v59, v67, v59, vcc
	s_waitcnt lgkmcnt(3)
	v_add_f32_e32 v68, v60, v68
	v_cndmask_b32_e32 v60, v68, v60, vcc
	s_waitcnt lgkmcnt(2)
	v_add_f32_e32 v69, v61, v69
	v_cndmask_b32_e32 v61, v69, v61, vcc
	s_waitcnt lgkmcnt(1)
	v_add_f32_e32 v70, v62, v70
	v_cndmask_b32_e32 v62, v70, v62, vcc
	s_waitcnt lgkmcnt(0)
	v_add_f32_e32 v71, v63, v71
	v_cndmask_b32_e32 v63, v71, v63, vcc
	ds_bpermute_b32 v64, v7, v56
	ds_bpermute_b32 v65, v7, v57
	ds_bpermute_b32 v66, v7, v58
	ds_bpermute_b32 v67, v7, v59
	ds_bpermute_b32 v68, v7, v60
	ds_bpermute_b32 v69, v7, v61
	ds_bpermute_b32 v70, v7, v62
	ds_bpermute_b32 v71, v7, v63
	s_waitcnt lgkmcnt(7)
	v_add_f32_e32 v64, v56, v64
	v_cndmask_b32_e64 v56, v56, v64, s[0:1]
	s_waitcnt lgkmcnt(6)
	v_add_f32_e32 v65, v57, v65
	v_cndmask_b32_e64 v57, v57, v65, s[0:1]
	s_waitcnt lgkmcnt(5)
	v_add_f32_e32 v66, v58, v66
	v_cndmask_b32_e64 v58, v58, v66, s[0:1]
	s_waitcnt lgkmcnt(4)
	v_add_f32_e32 v67, v59, v67
	v_cndmask_b32_e64 v59, v59, v67, s[0:1]
	s_waitcnt lgkmcnt(3)
	v_add_f32_e32 v68, v60, v68
	v_cndmask_b32_e64 v60, v60, v68, s[0:1]
	s_waitcnt lgkmcnt(2)
	v_add_f32_e32 v69, v61, v69
	v_cndmask_b32_e64 v61, v61, v69, s[0:1]
	s_waitcnt lgkmcnt(1)
	v_add_f32_e32 v70, v62, v70
	v_cndmask_b32_e64 v62, v62, v70, s[0:1]
	s_waitcnt lgkmcnt(0)
	v_add_f32_e32 v71, v63, v71
	v_cndmask_b32_e64 v63, v63, v71, s[0:1]
	ds_bpermute_b32 v64, v9, v56
	ds_bpermute_b32 v65, v9, v57
	ds_bpermute_b32 v66, v9, v58
	ds_bpermute_b32 v67, v9, v59
	ds_bpermute_b32 v68, v9, v60
	ds_bpermute_b32 v69, v9, v61
	ds_bpermute_b32 v70, v9, v62
	ds_bpermute_b32 v71, v9, v63
	v_lshl_add_u64 v[4:5], v[0:1], 0, s[8:9]
	v_mov_b32_e32 v72, v10
	s_waitcnt lgkmcnt(7)
	v_add_f32_e32 v73, v72, v64
	s_waitcnt lgkmcnt(6)
	v_add_f32_e32 v74, v73, v65
	s_waitcnt lgkmcnt(5)
	v_add_f32_e32 v75, v74, v66
	s_waitcnt lgkmcnt(4)
	v_add_f32_e32 v76, v75, v67
	s_waitcnt lgkmcnt(3)
	v_add_f32_e32 v77, v76, v68
	s_waitcnt lgkmcnt(2)
	v_add_f32_e32 v78, v77, v69
	s_waitcnt lgkmcnt(1)
	v_add_f32_e32 v79, v78, v70
	s_waitcnt lgkmcnt(0)
	v_add_f32_e32 v80, v79, v71
	v_mov_b32_e32 v10, v80
	v_add_f32_e32 v12, v72, v56
	v_mul_f32_e32 v13, 0xbfb8aa3b, v12
	v_bfe_u32 v14, v13, 16, 1
	v_add3_u32 v13, v13, v14, s12
	v_and_b32_e32 v14, 0xffff0000, v13
	v_fma_f32 v12, v12, s3, -v14
	v_bfe_u32 v14, v12, 16, 1
	v_add3_u32 v14, v12, v14, s12
	v_and_b32_e32 v14, 0xffff0000, v14
	v_sub_f32_e32 v15, v12, v14
	v_or_b32_sdwa v16, v14, v13 dst_sel:DWORD dst_unused:UNUSED_PAD src0_sel:DWORD src1_sel:WORD_1
	v_bfe_u32 v13, v15, 16, 1
	v_add3_u32 v13, v15, v13, s12
	v_lshrrev_b32_e32 v17, 16, v13
	global_store_dwordx2 v[4:5], v[16:17], off
	v_add_f32_e32 v12, v73, v57
	v_mul_f32_e32 v13, 0xbfb8aa3b, v12
	v_bfe_u32 v14, v13, 16, 1
	v_add3_u32 v13, v13, v14, s12
	v_and_b32_e32 v14, 0xffff0000, v13
	v_fma_f32 v12, v12, s3, -v14
	v_bfe_u32 v14, v12, 16, 1
	v_add3_u32 v14, v12, v14, s12
	v_and_b32_e32 v14, 0xffff0000, v14
	v_sub_f32_e32 v15, v12, v14
	v_or_b32_sdwa v18, v14, v13 dst_sel:DWORD dst_unused:UNUSED_PAD src0_sel:DWORD src1_sel:WORD_1
	v_bfe_u32 v13, v15, 16, 1
	v_add3_u32 v13, v15, v13, s12
	v_lshrrev_b32_e32 v19, 16, v13
	global_store_dwordx2 v[4:5], v[18:19], off offset:32
	v_add_f32_e32 v12, v74, v58
	v_mul_f32_e32 v13, 0xbfb8aa3b, v12
	v_bfe_u32 v14, v13, 16, 1
	v_add3_u32 v13, v13, v14, s12
	v_and_b32_e32 v14, 0xffff0000, v13
	v_fma_f32 v12, v12, s3, -v14
	v_bfe_u32 v14, v12, 16, 1
	v_add3_u32 v14, v12, v14, s12
	v_and_b32_e32 v14, 0xffff0000, v14
	v_sub_f32_e32 v15, v12, v14
	v_or_b32_sdwa v20, v14, v13 dst_sel:DWORD dst_unused:UNUSED_PAD src0_sel:DWORD src1_sel:WORD_1
	v_bfe_u32 v13, v15, 16, 1
	v_add3_u32 v13, v15, v13, s12
	v_lshrrev_b32_e32 v21, 16, v13
	global_store_dwordx2 v[4:5], v[20:21], off offset:64
	v_add_f32_e32 v12, v75, v59
	v_mul_f32_e32 v13, 0xbfb8aa3b, v12
	v_bfe_u32 v14, v13, 16, 1
	v_add3_u32 v13, v13, v14, s12
	v_and_b32_e32 v14, 0xffff0000, v13
	v_fma_f32 v12, v12, s3, -v14
	v_bfe_u32 v14, v12, 16, 1
	v_add3_u32 v14, v12, v14, s12
	v_and_b32_e32 v14, 0xffff0000, v14
	v_sub_f32_e32 v15, v12, v14
	v_or_b32_sdwa v22, v14, v13 dst_sel:DWORD dst_unused:UNUSED_PAD src0_sel:DWORD src1_sel:WORD_1
	v_bfe_u32 v13, v15, 16, 1
	v_add3_u32 v13, v15, v13, s12
	v_lshrrev_b32_e32 v23, 16, v13
	global_store_dwordx2 v[4:5], v[22:23], off offset:96
	v_add_f32_e32 v12, v76, v60
	v_mul_f32_e32 v13, 0xbfb8aa3b, v12
	v_bfe_u32 v14, v13, 16, 1
	v_add3_u32 v13, v13, v14, s12
	v_and_b32_e32 v14, 0xffff0000, v13
	v_fma_f32 v12, v12, s3, -v14
	v_bfe_u32 v14, v12, 16, 1
	v_add3_u32 v14, v12, v14, s12
	v_and_b32_e32 v14, 0xffff0000, v14
	v_sub_f32_e32 v15, v12, v14
	v_or_b32_sdwa v16, v14, v13 dst_sel:DWORD dst_unused:UNUSED_PAD src0_sel:DWORD src1_sel:WORD_1
	v_bfe_u32 v13, v15, 16, 1
	v_add3_u32 v13, v15, v13, s12
	v_lshrrev_b32_e32 v17, 16, v13
	global_store_dwordx2 v[4:5], v[16:17], off offset:128
	v_add_f32_e32 v12, v77, v61
	v_mul_f32_e32 v13, 0xbfb8aa3b, v12
	v_bfe_u32 v14, v13, 16, 1
	v_add3_u32 v13, v13, v14, s12
	v_and_b32_e32 v14, 0xffff0000, v13
	v_fma_f32 v12, v12, s3, -v14
	v_bfe_u32 v14, v12, 16, 1
	v_add3_u32 v14, v12, v14, s12
	v_and_b32_e32 v14, 0xffff0000, v14
	v_sub_f32_e32 v15, v12, v14
	v_or_b32_sdwa v18, v14, v13 dst_sel:DWORD dst_unused:UNUSED_PAD src0_sel:DWORD src1_sel:WORD_1
	v_bfe_u32 v13, v15, 16, 1
	v_add3_u32 v13, v15, v13, s12
	v_lshrrev_b32_e32 v19, 16, v13
	global_store_dwordx2 v[4:5], v[18:19], off offset:160
	v_add_f32_e32 v12, v78, v62
	v_mul_f32_e32 v13, 0xbfb8aa3b, v12
	v_bfe_u32 v14, v13, 16, 1
	v_add3_u32 v13, v13, v14, s12
	v_and_b32_e32 v14, 0xffff0000, v13
	v_fma_f32 v12, v12, s3, -v14
	v_bfe_u32 v14, v12, 16, 1
	v_add3_u32 v14, v12, v14, s12
	v_and_b32_e32 v14, 0xffff0000, v14
	v_sub_f32_e32 v15, v12, v14
	v_or_b32_sdwa v20, v14, v13 dst_sel:DWORD dst_unused:UNUSED_PAD src0_sel:DWORD src1_sel:WORD_1
	v_bfe_u32 v13, v15, 16, 1
	v_add3_u32 v13, v15, v13, s12
	v_lshrrev_b32_e32 v21, 16, v13
	global_store_dwordx2 v[4:5], v[20:21], off offset:192
	v_add_f32_e32 v12, v79, v63
	v_mul_f32_e32 v13, 0xbfb8aa3b, v12
	v_bfe_u32 v14, v13, 16, 1
	v_add3_u32 v13, v13, v14, s12
	v_and_b32_e32 v14, 0xffff0000, v13
	v_fma_f32 v12, v12, s3, -v14
	v_bfe_u32 v14, v12, 16, 1
	v_add3_u32 v14, v12, v14, s12
	v_and_b32_e32 v14, 0xffff0000, v14
	v_sub_f32_e32 v15, v12, v14
	v_or_b32_sdwa v22, v14, v13 dst_sel:DWORD dst_unused:UNUSED_PAD src0_sel:DWORD src1_sel:WORD_1
	v_bfe_u32 v13, v15, 16, 1
	v_add3_u32 v13, v15, v13, s12
	v_lshrrev_b32_e32 v23, 16, v13
	global_store_dwordx2 v[4:5], v[22:23], off offset:224
	s_add_u32 s8, s8, 0x100
	s_addc_u32 s9, s9, 0
	s_waitcnt vmcnt(40)
	global_load_dword v48, v[2:3], off offset:-1024
	global_load_dword v49, v[2:3], off offset:-768
	global_load_dword v50, v[2:3], off offset:-512
	global_load_dword v51, v[2:3], off offset:-256
	global_load_dword v52, v[2:3], off
	global_load_dword v53, v[2:3], off offset:256
	global_load_dword v54, v[2:3], off offset:512
	global_load_dword v55, v[2:3], off offset:768
	v_lshl_add_u64 v[2:3], v[2:3], 0, s[10:11]
	global_load_dword v56, v[2:3], off offset:-1024
	global_load_dword v57, v[2:3], off offset:-768
	global_load_dword v58, v[2:3], off offset:-512
	global_load_dword v59, v[2:3], off offset:-256
	global_load_dword v60, v[2:3], off
	global_load_dword v61, v[2:3], off offset:256
	global_load_dword v62, v[2:3], off offset:512
	global_load_dword v63, v[2:3], off offset:768
	v_lshl_add_u64 v[2:3], v[2:3], 0, s[10:11]
	s_cmpk_lg_i32 s8, 0x1000
	s_cbranch_scc1 .Lcs_loop
	s_waitcnt vmcnt(0)
	s_barrier
	s_branch .LBB0_763
